# diff-attention component-0 epilogue: O1 f32 scratch stored row-contiguous (2 rows x 512B per store instruction) instead of 64 scattered 16B pieces
# speedup vs baseline: 1.0149x; 1.0149x over previous
; #define SBAR() __builtin_amdgcn_sched_barrier(0)
; __device__ __forceinline__ int crow(int r, int hi) { return (r & 3) + 8 * (r >> 2) + 4 * hi; }
; #define PV_READ(S, D0) do { S##0 = tr_read<v_rd_off(D0, 0, 0)>(vb); S##1 = tr_read<v_rd_off(D0, 0, 1)>(vb); S##2 = tr_read<v_rd_off(D0, 1, 0)>(vb); S##3 = tr_read<v_rd_off(D0, 1, 1)>(vb); \
;     S##4 = tr_read<v_rd_off(D0, 2, 0)>(vb); S##5 = tr_read<v_rd_off(D0, 2, 1)>(vb); S##6 = tr_read<v_rd_off(D0, 3, 0)>(vb); S##7 = tr_read<v_rd_off(D0, 3, 1)>(vb); } while (0)
; #define PV_WAIT() do { asm volatile("s_waitcnt lgkmcnt(0)" ::: "memory"); SBAR(); } while (0)
; __device__ __forceinline__ void finishSM(f32x16& p0, f32x16& p1, float alpha, float& l_reg, bf16x8& pa0, bf16x8& pa1, bf16x8& pa2, bf16x8& pa3) {
; #pragma unroll
;   for (int r = 0; r < 16; ++r) p1[r] = __builtin_amdgcn_exp2f(p1[r]);
;   float ps = 0;
; #pragma unroll
;   for (int r = 0; r < 16; ++r) ps += p0[r];
; #pragma unroll
;   for (int r = 0; r < 16; ++r) ps += p1[r];
;   { auto rr = __builtin_amdgcn_permlane32_swap(__float_as_uint(ps), __float_as_uint(ps), false, false);
;     ps = __uint_as_float(rr[0]) + __uint_as_float(rr[1]); }
;   l_reg = l_reg * alpha + ps;
;     ...
;   PK4(p0, 0, pa0); PK4(p0, 8, pa1); PK4(p1, 0, pa2); PK4(p1, 8, pa3);
; __device__ __forceinline__ void pv_pipe(f32x16* o, int vb, bf16x8 pa0, bf16x8 pa1, bf16x8 pa2, bf16x8 pa3) {
;   s16x4 a0, a1, a2, a3, a4, a5, a6, a7, b0, b1, b2, b3, b4, b5, b6, b7;
;   PV_READ(a, 0); PV_WAIT();
;   PV_READ(b, 1); SBAR(); PV_MMA(o[0], a); PV_WAIT();
;   PV_READ(a, 2); SBAR(); PV_MMA(o[1], b); PV_WAIT();
;   PV_READ(b, 3); SBAR(); PV_MMA(o[2], a); PV_WAIT();
;   PV_MMA(o[3], b);
; }
; template <bool MLA> ...
;     ...
;     SBAR(); qkt_pre(pB0, pB1, KR_lds + bK * SHM_KR, qr, negm, r32, hi);
;     finishSM(pA0, pA1, alA, l_reg, pa0, pa1, pa2, pa3); SBAR();
;     PVF(o, vb0 + bV * SHM_V, pa0, pa1, pa2, pa3); partialSM_pre<false>(pB0, pB1, Mref, negm, alB);
;     RESC(alB);
;     finishSM(pB0, pB1, alB, l_reg, pa0, pa1, pa2, pa3); SBAR();
;     PVF(o, vb0 + bK * SHM_V, pa0, pa1, pa2, pa3);
;     ...
;   }
;   if (hi == 0) li_l[r32] = l_reg; asm volatile("s_waitcnt lgkmcnt(0)" ::: "memory");
; #pragma unroll
;   for (int r = 0; r < 16; ++r) rli[r] = __builtin_amdgcn_rcpf(li_l[crow(r, hi)]);
;   __syncthreads();
.LBB0_815:
	v_exp_f32_e32 v82, v98
	v_exp_f32_e32 v83, v99
	v_exp_f32_e32 v84, v100
	v_exp_f32_e32 v85, v101
	v_exp_f32_e32 v86, v102
	v_exp_f32_e32 v98, v66
	v_add_f32_e32 v66, 0, v82
	v_exp_f32_e32 v87, v103
	v_add_f32_e32 v66, v83, v66
	v_exp_f32_e32 v88, v104
	v_add_f32_e32 v66, v84, v66
	v_exp_f32_e32 v89, v105
	v_add_f32_e32 v66, v85, v66
	v_exp_f32_e32 v90, v106
	v_add_f32_e32 v66, v86, v66
	v_exp_f32_e32 v91, v107
	v_add_f32_e32 v66, v87, v66
	v_exp_f32_e32 v92, v108
	v_add_f32_e32 v66, v88, v66
	v_exp_f32_e32 v93, v109
	v_add_f32_e32 v66, v89, v66
	v_exp_f32_e32 v94, v110
	v_add_f32_e32 v66, v90, v66
	v_exp_f32_e32 v95, v111
	v_add_f32_e32 v66, v91, v66
	v_exp_f32_e32 v96, v112
	v_add_f32_e32 v66, v92, v66
	v_exp_f32_e32 v97, v113
	v_add_f32_e32 v66, v93, v66
	v_add_f32_e32 v66, v94, v66
	v_exp_f32_e32 v99, v67
	v_add_f32_e32 v66, v95, v66
	v_exp_f32_e32 v100, v68
	v_add_f32_e32 v66, v96, v66
	v_exp_f32_e32 v101, v69
	v_add_f32_e32 v66, v97, v66
	v_exp_f32_e32 v102, v70
	v_add_f32_e32 v66, v98, v66
	v_exp_f32_e32 v103, v71
	v_add_f32_e32 v66, v99, v66
	v_exp_f32_e32 v104, v72
	v_add_f32_e32 v66, v100, v66
	v_exp_f32_e32 v105, v73
	v_add_f32_e32 v66, v101, v66
	v_exp_f32_e32 v106, v74
	v_add_f32_e32 v66, v102, v66
	v_exp_f32_e32 v107, v75
	v_add_f32_e32 v66, v103, v66
	v_exp_f32_e32 v108, v76
	v_add_f32_e32 v66, v104, v66
	v_exp_f32_e32 v109, v77
	v_add_f32_e32 v66, v105, v66
	v_exp_f32_e32 v110, v78
	v_add_f32_e32 v66, v106, v66
	v_exp_f32_e32 v111, v79
	v_add_f32_e32 v66, v107, v66
	v_exp_f32_e32 v112, v80
	v_add_f32_e32 v66, v108, v66
	v_exp_f32_e32 v113, v81
	v_add_f32_e32 v66, v109, v66
	v_add_f32_e32 v66, v110, v66
	v_add_f32_e32 v66, v111, v66
	v_add_f32_e32 v66, v112, v66
	v_add_f32_e32 v66, v113, v66
	v_mov_b32_e32 v67, v66
	s_nop 1
	v_permlane32_swap_b32_e32 v66, v67
	v_cvt_pk_bf16_f32 v68, v82, v83
	v_cvt_pk_bf16_f32 v69, v84, v85
	v_cvt_pk_bf16_f32 v70, v86, v87
	v_cvt_pk_bf16_f32 v71, v88, v89
	v_cvt_pk_bf16_f32 v72, v90, v91
	v_cvt_pk_bf16_f32 v73, v92, v93
	v_cvt_pk_bf16_f32 v74, v94, v95
	v_cvt_pk_bf16_f32 v75, v96, v97
	v_cvt_pk_bf16_f32 v76, v98, v99
	v_cvt_pk_bf16_f32 v77, v100, v101
	v_cvt_pk_bf16_f32 v78, v102, v103
	v_cvt_pk_bf16_f32 v79, v104, v105
	v_cvt_pk_bf16_f32 v80, v106, v107
	v_cvt_pk_bf16_f32 v81, v108, v109
	v_cvt_pk_bf16_f32 v82, v110, v111
	v_cvt_pk_bf16_f32 v83, v112, v113
	v_permlane32_swap_b32_e32 v68, v70
	v_permlane32_swap_b32_e32 v69, v71
	v_permlane32_swap_b32_e32 v72, v74
	v_permlane32_swap_b32_e32 v73, v75
	v_permlane32_swap_b32_e32 v76, v78
	v_permlane32_swap_b32_e32 v77, v79
	v_permlane32_swap_b32_e32 v80, v82
	v_permlane32_swap_b32_e32 v81, v83
	ds_read_b64_tr_b16 v[84:85], v180 offset:0
	ds_read_b64_tr_b16 v[86:87], v180 offset:0x800
	ds_read_b64_tr_b16 v[88:89], v180 offset:0x1000
	ds_read_b64_tr_b16 v[90:91], v180 offset:0x1800
	ds_read_b64_tr_b16 v[92:93], v180 offset:0x2000
	ds_read_b64_tr_b16 v[94:95], v180 offset:0x2800
	ds_read_b64_tr_b16 v[96:97], v180 offset:0x3000
	ds_read_b64_tr_b16 v[98:99], v180 offset:0x3800
	s_waitcnt lgkmcnt(0)
	ds_read_b64_tr_b16 v[100:101], v180 offset:0x200
	ds_read_b64_tr_b16 v[102:103], v180 offset:0xa00
	ds_read_b64_tr_b16 v[104:105], v180 offset:0x1200
	ds_read_b64_tr_b16 v[106:107], v180 offset:0x1a00
	ds_read_b64_tr_b16 v[108:109], v180 offset:0x2200
	ds_read_b64_tr_b16 v[110:111], v180 offset:0x2a00
	ds_read_b64_tr_b16 v[118:119], v180 offset:0x3200
	ds_read_b64_tr_b16 v[120:121], v180 offset:0x3a00
	s_nop 0
	v_mfma_f32_32x32x16_bf16 v[2:17], v[68:71], v[84:87], v[2:17]
	s_waitcnt lgkmcnt(0)
	v_mfma_f32_32x32x16_bf16 v[2:17], v[72:75], v[88:91], v[2:17]
	v_mfma_f32_32x32x16_bf16 v[2:17], v[76:79], v[92:95], v[2:17]
	v_mfma_f32_32x32x16_bf16 v[2:17], v[80:83], v[96:99], v[2:17]
	ds_read_b64_tr_b16 v[84:85], v180 offset:0x400
	ds_read_b64_tr_b16 v[86:87], v180 offset:0xc00
	ds_read_b64_tr_b16 v[88:89], v180 offset:0x1400
	ds_read_b64_tr_b16 v[90:91], v180 offset:0x1c00
	ds_read_b64_tr_b16 v[92:93], v180 offset:0x2400
	ds_read_b64_tr_b16 v[94:95], v180 offset:0x2c00
	ds_read_b64_tr_b16 v[96:97], v180 offset:0x3400
	ds_read_b64_tr_b16 v[98:99], v180 offset:0x3c00
	v_mfma_f32_32x32x16_bf16 v[50:65], v[68:71], v[100:103], v[50:65]
	s_waitcnt lgkmcnt(0)
	v_mfma_f32_32x32x16_bf16 v[50:65], v[72:75], v[104:107], v[50:65]
	v_mfma_f32_32x32x16_bf16 v[50:65], v[76:79], v[108:111], v[50:65]
	v_mfma_f32_32x32x16_bf16 v[50:65], v[80:83], v[118:121], v[50:65]
	ds_read_b64_tr_b16 v[100:101], v180 offset:0x600
	ds_read_b64_tr_b16 v[102:103], v180 offset:0xe00
	ds_read_b64_tr_b16 v[104:105], v180 offset:0x1600
	ds_read_b64_tr_b16 v[106:107], v180 offset:0x1e00
	ds_read_b64_tr_b16 v[108:109], v180 offset:0x2600
	ds_read_b64_tr_b16 v[110:111], v180 offset:0x2e00
	ds_read_b64_tr_b16 v[118:119], v180 offset:0x3600
	ds_read_b64_tr_b16 v[120:121], v180 offset:0x3e00
	v_mfma_f32_32x32x16_bf16 v[34:49], v[68:71], v[84:87], v[34:49]
	s_waitcnt lgkmcnt(0)
	v_mfma_f32_32x32x16_bf16 v[34:49], v[72:75], v[88:91], v[34:49]
	v_mfma_f32_32x32x16_bf16 v[34:49], v[76:79], v[92:95], v[34:49]
	v_mfma_f32_32x32x16_bf16 v[34:49], v[80:83], v[96:99], v[34:49]
	v_mfma_f32_32x32x16_bf16 v[18:33], v[68:71], v[100:103], v[18:33]
	v_mfma_f32_32x32x16_bf16 v[18:33], v[72:75], v[104:107], v[18:33]
	v_mfma_f32_32x32x16_bf16 v[18:33], v[76:79], v[108:111], v[18:33]
	v_mfma_f32_32x32x16_bf16 v[18:33], v[80:83], v[118:121], v[18:33]
	s_and_saveexec_b64 s[10:11], s[38:39]
	v_add_f32_e32 v68, v114, v115
	v_fmac_f32_e32 v68, v182, v174
	v_add_f32_e32 v66, v66, v67
	v_fmac_f32_e32 v66, v68, v116
	ds_write_b32 v181, v66
	s_or_b64 exec, exec, s[10:11]
	s_waitcnt lgkmcnt(0)
	v_add_u32_e32 v74, s27, v160
	ds_read_b128 v[66:69], v74
	ds_read_b128 v[70:73], v74 offset:32
	s_and_b32 s10, s24, 0xf00
	s_add_u32 s8, s10, s8
	s_addc_u32 s9, 0, s9
	s_waitcnt lgkmcnt(1)
	v_rcp_f32_e32 v75, v66
	v_rcp_f32_e32 v76, v67
	v_rcp_f32_e32 v77, v68
	v_rcp_f32_e32 v78, v69
	s_waitcnt lgkmcnt(0)
	v_rcp_f32_e32 v79, v70
	ds_read_b128 v[66:69], v74 offset:64
	v_rcp_f32_e32 v80, v71
	v_rcp_f32_e32 v81, v72
	v_rcp_f32_e32 v82, v73
	ds_read_b128 v[70:73], v74 offset:96
	v_mov_b32_e32 v74, v0
	s_waitcnt lgkmcnt(0)
	s_barrier
; __device__ __forceinline__ int crow(int r, int hi) { return (r & 3) + 8 * (r >> 2) + 4 * hi; }
; __device__ __forceinline__ int opaque_tid() { int t = threadIdx.x; asm volatile("" : "+v"(t)); return t; }
; template <int MODE> __device__ __forceinline__ void attn_epilogue(char* lds, const att::f32x16 (&o)[4], const float (&rli)[16], float* o1, bf16raw* ob, float lam, float post, const float* gs) {
;     const int tid_ = opaque_tid(); const int lane = tid_ & 63, wave = tid_ >> 6, r32 = lane & 31, hi = lane >> 5;
;     float* st = (float*)(lds + wave * ATT_STAGE);
; #pragma unroll
;     for (int r = 0; r < 16; ++r) { const int orow = att::crow(r, hi);
; #pragma unroll
;         for (int d0 = 0; d0 < 4; ++d0) st[orow * 132 + d0 * 32 + r32] = o[d0][r] * rli[r]; }
;     asm volatile("s_waitcnt lgkmcnt(0)" ::: "memory");
;     float* sr = st + r32 * 132 + 64 * hi;
;     const size_t goff = (size_t)r32 * 1024 + 64 * hi, boff = (size_t)r32 * 2048 + 64 * hi;
	v_mul_f32_e32 v2, v2, v75
	v_lshrrev_b32_e32 v83, 6, v74
	v_and_b32_e32 v84, 31, v74
	v_bfe_u32 v74, v74, 5, 1
	v_mul_lo_u32 v83, v83, s75
	v_add_u32_e32 v83, 0, v83
	v_lshlrev_b32_e32 v85, 2, v84
	v_mul_u32_u24_e32 v86, 0x840, v74
	v_add3_u32 v85, v83, v85, v86
	v_mul_f32_e32 v50, v50, v75
	ds_write2_b32 v85, v2, v50 offset1:32
	v_mul_f32_e32 v2, v34, v75
	v_mul_f32_e32 v18, v18, v75
	ds_write2_b32 v85, v2, v18 offset0:64 offset1:96
	v_mul_f32_e32 v2, v3, v76
	v_mul_f32_e32 v3, v51, v76
	ds_write2_b32 v85, v2, v3 offset0:132 offset1:164
	v_mul_f32_e32 v2, v35, v76
	v_mul_f32_e32 v3, v19, v76
	ds_write2_b32 v85, v2, v3 offset0:196 offset1:228
	v_mul_f32_e32 v2, v4, v77
	v_mul_f32_e32 v3, v52, v77
	v_add_u32_e32 v4, 0x400, v85
	ds_write2_b32 v4, v2, v3 offset0:8 offset1:40
	v_mul_f32_e32 v2, v36, v77
	v_mul_f32_e32 v3, v20, v77
	ds_write2_b32 v4, v2, v3 offset0:72 offset1:104
	v_mul_f32_e32 v2, v5, v78
	v_mul_f32_e32 v3, v53, v78
	ds_write2_b32 v4, v2, v3 offset0:140 offset1:172
	v_mul_f32_e32 v2, v37, v78
	v_mul_f32_e32 v3, v21, v78
	ds_write2_b32 v4, v2, v3 offset0:204 offset1:236
	v_mul_f32_e32 v2, v6, v79
	v_mul_f32_e32 v3, v54, v79
	v_add_u32_e32 v4, 0x1000, v85
	ds_write2_b32 v4, v2, v3 offset0:32 offset1:64
	v_mul_f32_e32 v2, v38, v79
	v_mul_f32_e32 v3, v22, v79
	ds_write2_b32 v4, v2, v3 offset0:96 offset1:128
	v_mul_f32_e32 v2, v7, v80
	v_mul_f32_e32 v3, v55, v80
	ds_write2_b32 v4, v2, v3 offset0:164 offset1:196
	v_mul_f32_e32 v2, v39, v80
	v_mul_f32_e32 v3, v23, v80
	v_add_u32_e32 v4, 0x1200, v85
	v_rcp_f32_e32 v66, v66
	ds_write2_b32 v4, v2, v3 offset0:100 offset1:132
	v_mul_f32_e32 v2, v8, v81
	v_mul_f32_e32 v3, v56, v81
	v_add_u32_e32 v4, 0x1400, v85
	ds_write2_b32 v4, v2, v3 offset0:40 offset1:72
	v_mul_f32_e32 v2, v40, v81
	v_mul_f32_e32 v3, v24, v81
	v_rcp_f32_e32 v67, v67
	ds_write2_b32 v4, v2, v3 offset0:104 offset1:136
	v_mul_f32_e32 v2, v9, v82
	v_mul_f32_e32 v3, v57, v82
	ds_write2_b32 v4, v2, v3 offset0:172 offset1:204
	v_mul_f32_e32 v2, v41, v82
	v_mul_f32_e32 v3, v25, v82
	v_add_u32_e32 v4, 0x1600, v85
	v_rcp_f32_e32 v68, v68
	ds_write2_b32 v4, v2, v3 offset0:108 offset1:140
	v_mul_f32_e32 v2, v10, v66
	v_mul_f32_e32 v3, v58, v66
	v_add_u32_e32 v4, 0x2000, v85
	ds_write2_b32 v4, v2, v3 offset0:64 offset1:96
	v_mul_f32_e32 v2, v42, v66
	v_mul_f32_e32 v3, v26, v66
	v_rcp_f32_e32 v69, v69
	ds_write2_b32 v4, v2, v3 offset0:128 offset1:160
	v_mul_f32_e32 v2, v11, v67
	v_mul_f32_e32 v3, v59, v67
	ds_write2_b32 v4, v2, v3 offset0:196 offset1:228
	v_mul_f32_e32 v2, v43, v67
	v_mul_f32_e32 v3, v27, v67
	v_add_u32_e32 v4, 0x2400, v85
	v_rcp_f32_e32 v70, v70
	ds_write2_b32 v4, v2, v3 offset0:4 offset1:36
	v_mul_f32_e32 v2, v12, v68
	v_mul_f32_e32 v3, v60, v68
	ds_write2_b32 v4, v2, v3 offset0:72 offset1:104
	v_mul_f32_e32 v2, v44, v68
	v_mul_f32_e32 v3, v28, v68
	v_rcp_f32_e32 v71, v71
	ds_write2_b32 v4, v2, v3 offset0:136 offset1:168
	v_mul_f32_e32 v2, v13, v69
	v_mul_f32_e32 v3, v61, v69
	ds_write2_b32 v4, v2, v3 offset0:204 offset1:236
	v_mul_f32_e32 v2, v45, v69
	v_mul_f32_e32 v3, v29, v69
	v_add_u32_e32 v4, 0x2800, v85
	v_rcp_f32_e32 v72, v72
	ds_write2_b32 v4, v2, v3 offset0:12 offset1:44
	v_mul_f32_e32 v2, v14, v70
	v_mul_f32_e32 v3, v62, v70
	v_add_u32_e32 v4, 0x3000, v85
	ds_write2_b32 v4, v2, v3 offset0:96 offset1:128
	v_mul_f32_e32 v2, v46, v70
	v_mul_f32_e32 v3, v30, v70
	v_rcp_f32_e32 v73, v73
	ds_write2_b32 v4, v2, v3 offset0:160 offset1:192
	v_mul_f32_e32 v2, v15, v71
	v_mul_f32_e32 v3, v63, v71
	v_add_u32_e32 v4, 0x3200, v85
	ds_write2_b32 v4, v2, v3 offset0:100 offset1:132
	v_mul_f32_e32 v2, v47, v71
	v_mul_f32_e32 v3, v31, v71
	v_add_u32_e32 v4, 0x3400, v85
	ds_write2_b32 v4, v2, v3 offset0:36 offset1:68
	v_mul_f32_e32 v2, v16, v72
	v_mul_f32_e32 v3, v64, v72
	ds_write2_b32 v4, v2, v3 offset0:104 offset1:136
	v_mul_f32_e32 v2, v48, v72
	v_mul_f32_e32 v3, v32, v72
	ds_write2_b32 v4, v2, v3 offset0:168 offset1:200
	v_mul_f32_e32 v2, v17, v73
	v_mul_f32_e32 v3, v65, v73
	v_add_u32_e32 v4, 0x3600, v85
	ds_write2_b32 v4, v2, v3 offset0:108 offset1:140
	v_mul_f32_e32 v2, v49, v73
	v_mul_f32_e32 v3, v33, v73
	v_add_u32_e32 v4, 0x3800, v85
	ds_write2_b32 v4, v2, v3 offset0:44 offset1:76
	v_mul_u32_u24_e32 v2, 0x210, v74
	v_lshlrev_b32_e32 v5, 4, v84
	v_add3_u32 v4, v83, v2, v5
	v_lshl_add_u64 v[2:3], s[8:9], 0, v[158:159]
	v_lshlrev_b64 v[2:3], 12, v[2:3]
	s_waitcnt lgkmcnt(0)
; template <int MODE> __device__ __forceinline__ void attn_epilogue(char* lds, const att::f32x16 (&o)[4], const float (&rli)[16], float* o1, bf16raw* ob, float lam, float post, const float* gs) {
;     ...
;     float* sr = st + r32 * 132 + 64 * hi;
;     const size_t goff = (size_t)r32 * 1024 + 64 * hi, boff = (size_t)r32 * 2048 + 64 * hi;
;     if constexpr (MODE == 0) {
; #pragma unroll 4
;         for (int j = 0; j < 16; ++j) *(f32x4*)(o1 + goff + 4 * j) = *(const f32x4*)(sr + 4 * j);
; __global__ void __launch_bounds__(512, 2) mega_fwd(Args a) {
;     ...
;             for (int I = vcu; I < 512; I += G) {
;                 const int bh = I >> 4, qb = I & 15, b = bh >> 3, h = bh & 7;
;                 const size_t row0 = (size_t)b * SEQ, q0 = row0 + (size_t)qb * 256;
;                 att::f32x16 o[4]; float rli[16];
;                 att::attn_core<false>(Z + q0 * 3072 + (2 * h) * 64, 3072, nullptr, 0, Z + row0 * 3072 + 1024 + (2 * h) * 64, 3072, Z + row0 * 3072 + 2048 + h * 128, 3072, SEQ, (char*)lds, o, rli);
;                 attn_epilogue<0>((char*)lds, o, rli, xout + (q0 + wave * 32) * 1024 + h * 128, nullptr, 0.f, 0.f, nullptr);
;             }
	v_lshl_or_b32 v2, s26, 9, v2
	v_lshl_or_b32 v160, v74, 12, v5
	v_lshl_add_u64 v[2:3], v[2:3], 0, v[160:161]
	v_lshl_add_u64 v[2:3], s[0:1], 0, v[2:3]
	s_mov_b32 s98, 0x2000
	s_mov_b32 s99, 0
	ds_read_b128 v[6:9], v4
	ds_read_b128 v[10:13], v4 offset:1056
	ds_read_b128 v[14:17], v4 offset:2112
	ds_read_b128 v[18:21], v4 offset:3168
	s_waitcnt lgkmcnt(3)
	global_store_dwordx4 v[2:3], v[6:9], off offset:-32
	s_nop 0
	v_lshl_add_u64 v[2:3], v[2:3], 0, s[98:99]
	s_waitcnt lgkmcnt(2)
	global_store_dwordx4 v[2:3], v[10:13], off offset:-32
	s_nop 0
	v_lshl_add_u64 v[2:3], v[2:3], 0, s[98:99]
	s_waitcnt lgkmcnt(1)
	global_store_dwordx4 v[2:3], v[14:17], off offset:-32
	s_nop 0
	v_lshl_add_u64 v[2:3], v[2:3], 0, s[98:99]
	s_waitcnt lgkmcnt(0)
	global_store_dwordx4 v[2:3], v[18:21], off offset:-32
	s_nop 0
	v_lshl_add_u64 v[2:3], v[2:3], 0, s[98:99]
	ds_read_b128 v[6:9], v4 offset:4224
	ds_read_b128 v[10:13], v4 offset:5280
	ds_read_b128 v[14:17], v4 offset:6336
	ds_read_b128 v[18:21], v4 offset:7392
	s_waitcnt lgkmcnt(3)
	global_store_dwordx4 v[2:3], v[6:9], off offset:-32
	s_nop 0
	v_lshl_add_u64 v[2:3], v[2:3], 0, s[98:99]
	s_waitcnt lgkmcnt(2)
	global_store_dwordx4 v[2:3], v[10:13], off offset:-32
	s_nop 0
	v_lshl_add_u64 v[2:3], v[2:3], 0, s[98:99]
	s_waitcnt lgkmcnt(1)
	global_store_dwordx4 v[2:3], v[14:17], off offset:-32
	s_nop 0
	v_lshl_add_u64 v[2:3], v[2:3], 0, s[98:99]
	s_waitcnt lgkmcnt(0)
	global_store_dwordx4 v[2:3], v[18:21], off offset:-32
	s_nop 0
	v_lshl_add_u64 v[2:3], v[2:3], 0, s[98:99]
	ds_read_b128 v[6:9], v4 offset:8448
	ds_read_b128 v[10:13], v4 offset:9504
	ds_read_b128 v[14:17], v4 offset:10560
	ds_read_b128 v[18:21], v4 offset:11616
	s_waitcnt lgkmcnt(3)
	global_store_dwordx4 v[2:3], v[6:9], off offset:-32
	s_nop 0
	v_lshl_add_u64 v[2:3], v[2:3], 0, s[98:99]
	s_waitcnt lgkmcnt(2)
	global_store_dwordx4 v[2:3], v[10:13], off offset:-32
	s_nop 0
	v_lshl_add_u64 v[2:3], v[2:3], 0, s[98:99]
	s_waitcnt lgkmcnt(1)
	global_store_dwordx4 v[2:3], v[14:17], off offset:-32
	s_nop 0
	v_lshl_add_u64 v[2:3], v[2:3], 0, s[98:99]
	s_waitcnt lgkmcnt(0)
	global_store_dwordx4 v[2:3], v[18:21], off offset:-32
	s_nop 0
	v_lshl_add_u64 v[2:3], v[2:3], 0, s[98:99]
	ds_read_b128 v[6:9], v4 offset:12672
	ds_read_b128 v[10:13], v4 offset:13728
	ds_read_b128 v[14:17], v4 offset:14784
	ds_read_b128 v[18:21], v4 offset:15840
	s_waitcnt lgkmcnt(3)
	global_store_dwordx4 v[2:3], v[6:9], off offset:-32
	s_nop 0
	v_lshl_add_u64 v[2:3], v[2:3], 0, s[98:99]
	s_waitcnt lgkmcnt(2)
	global_store_dwordx4 v[2:3], v[10:13], off offset:-32
	s_nop 0
	v_lshl_add_u64 v[2:3], v[2:3], 0, s[98:99]
	s_waitcnt lgkmcnt(1)
	global_store_dwordx4 v[2:3], v[14:17], off offset:-32
	s_nop 0
	v_lshl_add_u64 v[2:3], v[2:3], 0, s[98:99]
	s_waitcnt lgkmcnt(0)
	global_store_dwordx4 v[2:3], v[18:21], off offset:-32
	s_nop 0
	v_lshl_add_u64 v[2:3], v[2:3], 0, s[98:99]
	s_add_i32 s4, s4, s73
	s_add_i32 s22, s22, s23
	s_add_i32 s24, s24, s25
	s_cmpk_gt_i32 s4, 0x1ff
	s_barrier
	s_cbranch_scc0 .LBB0_793
	s_branch .LBB0_821
